# late weight conversion rebalanced: phase 8 one ffn_w_up item per wave, phase 9 the rest of ffn_w_up and ffn_w_down
# baseline (speedup 1.0000x reference)
.LBB0_1914:
	s_waitcnt vmcnt(0)
	s_barrier
	s_cmp_gt_i32 s48, 32
	s_cbranch_scc0 .Ltr_skip8
	s_cmp_lt_u32 s2, 32
	s_cbranch_scc1 .Ltr_skip8
	s_sub_i32 s0, s2, 32
	v_lshl_add_u32 v92, s0, 3, v179
	v_add_u32_e32 v92, 0x200, v92
	s_movk_i32 s99, 0x8ff
	s_mov_b32 s3, 32
	s_mov_b32 s98, 8
	s_branch .Ltr_late_entry

.LBB0_2017:
	s_waitcnt vmcnt(0)
	s_barrier
	s_cmp_gt_i32 s48, 32
	s_cbranch_scc0 .Ltr_skip9
	s_cmp_lt_u32 s2, 32
	s_cbranch_scc1 .Ltr_skip9
	s_sub_i32 s0, s2, 32
	v_lshl_add_u32 v92, s0, 3, v179
	v_add_u32_e32 v92, 0x900, v92
	s_movk_i32 s99, 0x127f
	s_mov_b32 s3, 32
	s_mov_b32 s98, 9
	s_branch .Ltr_late_entry
